# attention local-tile QK^T: K/Q fragment ds_reads software-pipelined 5 deep over dead registers (was read-pair -> lgkmcnt(0) -> MFMA x8)
# baseline (speedup 1.0000x reference)
; #define LAS __attribute__((address_space(3)))
; template <int NKB> ...
;     ...
;     for (int kb = 0; kb < NKB; ++kb) {
; #pragma unroll
;         for (int e = 0; e < 16; ++e) s[kb][e] = 0.f;
; #pragma unroll
;         for (int kk = 0; kk < 8; ++kk) { const bf16x8 kf = *(const LAS bf16x8*)(kb_ + kb * 32 * KST + kk * 32); const bf16x8 qv = *(const LAS bf16x8*)(qb_ + kk * 32);
;             s[kb] = __builtin_amdgcn_mfma_f32_32x32x16_bf16(kf, qv, s[kb], 0, 0, 0); }
;     }
;     float mx = -3.0e38f;
;     if (NKB == 1) {
;         const LAS unsigned char* bp = (const LAS unsigned char*)bt + (ib & 3) * (ATT_BCS * 4) + (ib & ~3) * 4;
;         const float NEG = -__builtin_inff();
; #pragma unroll
;         for (int g4 = 0; g4 < 4; ++g4) { const f32x4 bias = *(const LAS f32x4*)(bp + (8 * g4) * 4);
; #pragma unroll
;             for (int i = 0; i < 4; ++i) { const int e = 4 * g4 + i, ko = 8 * g4 + i;
;                 const bool valid = rowact && (unsigned)(kc0 + ko) < 16u;
;                 const float v = valid ? (s[0][e] * c1 + bias[i]) : NEG; s[0][e] = v; mx = fmaxf(mx, v); } }
;     } else {
; #pragma unroll
;         for (int kb = 0; kb < NKB; ++kb)
; #pragma unroll
;             for (int e = 0; e < 16; ++e) { const float v = s[kb][e] * c1; s[kb][e] = v; mx = fmaxf(mx, v); }
;     }
;     mx = fmaxf(mx, __shfl_xor(mx, 32));
;     const float mnew = fmaxf(m, mx), alpha = __builtin_amdgcn_exp2f(m - mnew); m = mnew;
;     float ps = 0.f;
; #pragma unroll
;     for (int kb = 0; kb < NKB; ++kb)
; #pragma unroll
;         for (int e = 0; e < 16; ++e) { const float p = __builtin_amdgcn_exp2f(s[kb][e] - mnew); s[kb][e] = p; ps += p; }
;     l = l * alpha + ps;
;     if (__builtin_amdgcn_ballot_w64(alpha != 1.0f) != 0ull) {
; #pragma unroll
;         for (int db = 0; db < 4; ++db)
; #pragma unroll
;             for (int e = 0; e < 16; ++e) o[db][e] *= alpha;
.LBB0_214:
	s_add_i32 s80, s79, s65
	s_and_b64 vcc, exec, s[46:47]
	s_cbranch_vccz .LBB0_221
	s_add_i32 s44, s80, -3
	s_cmp_ge_u32 s44, s5
	s_cselect_b64 s[46:47], -1, 0
	s_cmp_lt_u32 s44, s89
	s_cselect_b64 vcc, -1, 0
	s_and_b64 s[46:47], s[46:47], vcc
	s_andn2_b64 vcc, exec, s[46:47]
	s_cbranch_vccnz .LBB0_219
	v_add_u32_e32 v90, s95, v179
	v_add_u32_e32 v91, v175, v177
	ds_read_b128 v[94:97], v90
	ds_read_b128 v[98:101], v91
	ds_read_b128 v[102:105], v90 offset:32
	ds_read_b128 v[106:109], v91 offset:32
	ds_read_b128 v[110:113], v90 offset:64
	ds_read_b128 v[114:117], v91 offset:64
	ds_read_b128 v[118:121], v90 offset:96
	ds_read_b128 v[122:125], v91 offset:96
	ds_read_b128 v[82:85], v90 offset:128
	ds_read_b128 v[86:89], v91 offset:128
	s_waitcnt lgkmcnt(8)
	v_mfma_f32_32x32x16_bf16 v[66:81], v[94:97], v[98:101], 0
	ds_read_b128 v[94:97], v90 offset:160
	ds_read_b128 v[98:101], v91 offset:160
	v_add_u32_e32 v1, v191, v194
	v_and_b32_e32 v1, 3, v1
	v_mul_u32_u24_e32 v1, 0x980, v1
	v_cmp_ge_u32_e32 vcc, s44, v131
	v_cmp_lt_u32_e64 s[46:47], s44, v190
	s_and_b64 s[46:47], vcc, s[46:47]
	s_and_b64 vcc, s[10:11], s[46:47]
	s_waitcnt lgkmcnt(8)
	v_mfma_f32_32x32x16_bf16 v[66:81], v[102:105], v[106:109], v[66:81]
	ds_read_b128 v[102:105], v90 offset:192
	ds_read_b128 v[106:109], v91 offset:192
	s_waitcnt lgkmcnt(8)
	v_mfma_f32_32x32x16_bf16 v[66:81], v[110:113], v[114:117], v[66:81]
	ds_read_b128 v[110:113], v90 offset:224
	ds_read_b128 v[114:117], v91 offset:224
	s_waitcnt lgkmcnt(8)
	v_mfma_f32_32x32x16_bf16 v[66:81], v[118:121], v[122:125], v[66:81]
	s_waitcnt lgkmcnt(6)
	v_mfma_f32_32x32x16_bf16 v[66:81], v[82:85], v[86:89], v[66:81]
	s_waitcnt lgkmcnt(4)
	v_mfma_f32_32x32x16_bf16 v[66:81], v[94:97], v[98:101], v[66:81]
	s_waitcnt lgkmcnt(2)
	v_mfma_f32_32x32x16_bf16 v[66:81], v[102:105], v[106:109], v[66:81]
	s_waitcnt lgkmcnt(0)
	v_mfma_f32_32x32x16_bf16 v[66:81], v[110:113], v[114:117], v[66:81]
	v_add_u32_e32 v82, 0x4a0, v193
	v_and_b32_e32 v82, -16, v82
	v_add3_u32 v1, s88, v1, v82
	ds_read_b128 v[86:89], v1
	ds_read_b128 v[90:93], v1 offset:32
	s_waitcnt lgkmcnt(1)
	s_nop 5
	v_fmamk_f32 v66, v66, 0x3e0293ee, v86
	v_cndmask_b32_e32 v85, v224, v66, vcc
	s_and_b64 vcc, s[46:47], s[12:13]
	v_fmamk_f32 v66, v67, 0x3e0293ee, v87
	v_cndmask_b32_e32 v84, v224, v66, vcc
	s_and_b64 vcc, s[46:47], s[14:15]
	v_fmamk_f32 v67, v68, 0x3e0293ee, v88
	v_cndmask_b32_e32 v83, v224, v67, vcc
	s_and_b64 vcc, s[46:47], s[16:17]
	v_fmac_f32_e32 v89, 0x3e0293ee, v69
	v_cndmask_b32_e32 v82, v224, v89, vcc
	ds_read_b128 v[86:89], v1 offset:64
	s_and_b64 vcc, s[46:47], s[18:19]
	s_waitcnt lgkmcnt(1)
	v_fmamk_f32 v67, v70, 0x3e0293ee, v90
	v_cndmask_b32_e32 v70, v224, v67, vcc
	s_and_b64 vcc, s[46:47], s[20:21]
	v_fmamk_f32 v67, v71, 0x3e0293ee, v91
	v_cndmask_b32_e32 v69, v224, v67, vcc
	s_and_b64 vcc, s[46:47], s[22:23]
	v_fmamk_f32 v67, v72, 0x3e0293ee, v92
	v_cndmask_b32_e32 v68, v224, v67, vcc
	s_and_b64 vcc, s[46:47], s[24:25]
	v_fmac_f32_e32 v93, 0x3e0293ee, v73
	v_cndmask_b32_e32 v67, v224, v93, vcc
	s_and_b64 vcc, s[26:27], s[46:47]
	s_waitcnt lgkmcnt(0)
	v_fmamk_f32 v71, v74, 0x3e0293ee, v86
	v_cndmask_b32_e32 v74, v224, v71, vcc
	s_and_b64 vcc, s[46:47], s[28:29]
	v_fmamk_f32 v71, v75, 0x3e0293ee, v87
	v_cndmask_b32_e32 v73, v224, v71, vcc
	s_and_b64 vcc, s[46:47], s[30:31]
	v_fmamk_f32 v71, v76, 0x3e0293ee, v88
	v_cndmask_b32_e32 v72, v224, v71, vcc
	s_and_b64 vcc, s[46:47], s[34:35]
	v_fmac_f32_e32 v89, 0x3e0293ee, v77
	v_cndmask_b32_e32 v71, v224, v89, vcc
	ds_read_b128 v[86:89], v1 offset:96
	v_max3_f32 v66, v85, s93, v84
	v_max3_f32 v66, v66, v83, v82
	v_max3_f32 v66, v66, v70, v69
	v_max3_f32 v66, v66, v68, v67
	s_and_b64 vcc, s[46:47], s[36:37]
	s_waitcnt lgkmcnt(0)
	v_fmamk_f32 v1, v78, 0x3e0293ee, v86
	v_max3_f32 v66, v66, v74, v73
	v_cndmask_b32_e32 v77, v224, v1, vcc
	s_and_b64 vcc, s[46:47], s[38:39]
	v_fmamk_f32 v1, v79, 0x3e0293ee, v87
	v_max3_f32 v66, v66, v72, v71
	v_cndmask_b32_e32 v75, v224, v1, vcc
	v_max3_f32 v1, v66, v77, v75
	s_and_b64 vcc, s[46:47], s[40:41]
	v_fmamk_f32 v66, v80, 0x3e0293ee, v88
	v_cndmask_b32_e32 v76, v224, v66, vcc
	s_and_b64 vcc, s[46:47], s[42:43]
	v_fmac_f32_e32 v89, 0x3e0293ee, v81
	v_cndmask_b32_e32 v78, v224, v89, vcc
	v_cmp_lt_i32_e32 vcc, v223, v225
	v_max3_f32 v1, v1, v76, v78
	s_nop 0
	v_cndmask_b32_e32 v66, v217, v223, vcc
	v_lshlrev_b32_e32 v66, 2, v66
	ds_bpermute_b32 v66, v66, v1
	s_waitcnt lgkmcnt(0)
	v_max3_f32 v1, v195, v1, v66
	v_sub_f32_e32 v66, v195, v1
	v_exp_f32_e32 v66, v66
	s_nop 0
	v_cmp_neq_f32_e32 vcc, 1.0, v66
	s_cbranch_vccz .LBB0_218
	v_pk_mul_f32 v[16:17], v[16:17], v[66:67] op_sel_hi:[1,0]
	v_pk_mul_f32 v[14:15], v[14:15], v[66:67] op_sel_hi:[1,0]
	v_pk_mul_f32 v[12:13], v[12:13], v[66:67] op_sel_hi:[1,0]
	v_pk_mul_f32 v[10:11], v[10:11], v[66:67] op_sel_hi:[1,0]
	v_pk_mul_f32 v[8:9], v[8:9], v[66:67] op_sel_hi:[1,0]
	v_pk_mul_f32 v[6:7], v[6:7], v[66:67] op_sel_hi:[1,0]
	v_pk_mul_f32 v[4:5], v[4:5], v[66:67] op_sel_hi:[1,0]
	v_pk_mul_f32 v[2:3], v[2:3], v[66:67] op_sel_hi:[1,0]
	v_pk_mul_f32 v[32:33], v[32:33], v[66:67] op_sel_hi:[1,0]
	v_pk_mul_f32 v[30:31], v[30:31], v[66:67] op_sel_hi:[1,0]
	v_pk_mul_f32 v[28:29], v[28:29], v[66:67] op_sel_hi:[1,0]
	v_pk_mul_f32 v[26:27], v[26:27], v[66:67] op_sel_hi:[1,0]
	v_pk_mul_f32 v[24:25], v[24:25], v[66:67] op_sel_hi:[1,0]
	v_pk_mul_f32 v[22:23], v[22:23], v[66:67] op_sel_hi:[1,0]
	v_pk_mul_f32 v[20:21], v[20:21], v[66:67] op_sel_hi:[1,0]
	v_pk_mul_f32 v[18:19], v[18:19], v[66:67] op_sel_hi:[1,0]
	v_pk_mul_f32 v[48:49], v[48:49], v[66:67] op_sel_hi:[1,0]
	v_pk_mul_f32 v[46:47], v[46:47], v[66:67] op_sel_hi:[1,0]
	v_pk_mul_f32 v[44:45], v[44:45], v[66:67] op_sel_hi:[1,0]
	v_pk_mul_f32 v[42:43], v[42:43], v[66:67] op_sel_hi:[1,0]
	v_pk_mul_f32 v[40:41], v[40:41], v[66:67] op_sel_hi:[1,0]
	v_pk_mul_f32 v[38:39], v[38:39], v[66:67] op_sel_hi:[1,0]
	v_pk_mul_f32 v[36:37], v[36:37], v[66:67] op_sel_hi:[1,0]
	v_pk_mul_f32 v[34:35], v[34:35], v[66:67] op_sel_hi:[1,0]
	v_pk_mul_f32 v[64:65], v[64:65], v[66:67] op_sel_hi:[1,0]
	v_pk_mul_f32 v[62:63], v[62:63], v[66:67] op_sel_hi:[1,0]
	v_pk_mul_f32 v[60:61], v[60:61], v[66:67] op_sel_hi:[1,0]
	v_pk_mul_f32 v[58:59], v[58:59], v[66:67] op_sel_hi:[1,0]
	v_pk_mul_f32 v[56:57], v[56:57], v[66:67] op_sel_hi:[1,0]
	v_pk_mul_f32 v[54:55], v[54:55], v[66:67] op_sel_hi:[1,0]
	v_pk_mul_f32 v[52:53], v[52:53], v[66:67] op_sel_hi:[1,0]
	v_pk_mul_f32 v[50:51], v[50:51], v[66:67] op_sel_hi:[1,0]

; #define LAS __attribute__((address_space(3)))
; template <int NKB> ...
;     ...
;     for (int kb = 0; kb < NKB; ++kb) {
; #pragma unroll
;         for (int e = 0; e < 16; ++e) s[kb][e] = 0.f;
; #pragma unroll
;         for (int kk = 0; kk < 8; ++kk) { const bf16x8 kf = *(const LAS bf16x8*)(kb_ + kb * 32 * KST + kk * 32); const bf16x8 qv = *(const LAS bf16x8*)(qb_ + kk * 32);
;             s[kb] = __builtin_amdgcn_mfma_f32_32x32x16_bf16(kf, qv, s[kb], 0, 0, 0); }
;     }
;     float mx = -3.0e38f;
;     if (NKB == 1) {
;         const LAS unsigned char* bp = (const LAS unsigned char*)bt + (ib & 3) * (ATT_BCS * 4) + (ib & ~3) * 4;
;         const float NEG = -__builtin_inff();
; #pragma unroll
;         for (int g4 = 0; g4 < 4; ++g4) { const f32x4 bias = *(const LAS f32x4*)(bp + (8 * g4) * 4);
; #pragma unroll
;             for (int i = 0; i < 4; ++i) { const int e = 4 * g4 + i, ko = 8 * g4 + i;
;                 const bool valid = rowact && (unsigned)(kc0 + ko) < 16u;
;                 const float v = valid ? (s[0][e] * c1 + bias[i]) : NEG; s[0][e] = v; mx = fmaxf(mx, v); } }
;     } else {
; #pragma unroll
;         for (int kb = 0; kb < NKB; ++kb)
; #pragma unroll
;             for (int e = 0; e < 16; ++e) { const float v = s[kb][e] * c1; s[kb][e] = v; mx = fmaxf(mx, v); }
;     }
;     mx = fmaxf(mx, __shfl_xor(mx, 32));
;     const float mnew = fmaxf(m, mx), alpha = __builtin_amdgcn_exp2f(m - mnew); m = mnew;
;     float ps = 0.f;
; #pragma unroll
;     for (int kb = 0; kb < NKB; ++kb)
; #pragma unroll
;         for (int e = 0; e < 16; ++e) { const float p = __builtin_amdgcn_exp2f(s[kb][e] - mnew); s[kb][e] = p; ps += p; }
;     l = l * alpha + ps;
;     if (__builtin_amdgcn_ballot_w64(alpha != 1.0f) != 0ull) {
; #pragma unroll
;         for (int db = 0; db < 4; ++db)
; #pragma unroll
;             for (int e = 0; e < 16; ++e) o[db][e] *= alpha;
.LBB0_232:
	s_and_b64 vcc, exec, s[46:47]
	s_cbranch_vccz .LBB0_240
	s_add_i32 s80, s80, -2
	s_cmp_ge_u32 s80, s5
	s_cselect_b64 s[44:45], -1, 0
	s_cmp_lt_u32 s80, s89
	s_cselect_b64 s[46:47], -1, 0
	s_and_b64 s[44:45], s[44:45], s[46:47]
	s_andn2_b64 vcc, exec, s[44:45]
	s_cbranch_vccnz .LBB0_238
	v_add_u32_e32 v27, s95, v179
	v_add_u32_e32 v28, v175, v177
	ds_read_b128 v[32:35], v27 offset:17408
	ds_read_b128 v[36:39], v28
	ds_read_b128 v[40:43], v27 offset:17440
	ds_read_b128 v[44:47], v28 offset:32
	ds_read_b128 v[48:51], v27 offset:17472
	ds_read_b128 v[52:55], v28 offset:64
	ds_read_b128 v[56:59], v27 offset:17504
	ds_read_b128 v[60:63], v28 offset:96
	ds_read_b128 v[18:21], v27 offset:17536
	ds_read_b128 v[22:25], v28 offset:128
	s_waitcnt lgkmcnt(8)
	v_mfma_f32_32x32x16_bf16 v[2:17], v[32:35], v[36:39], 0
	ds_read_b128 v[32:35], v27 offset:17568
	ds_read_b128 v[36:39], v28 offset:160
	v_add_u32_e32 v26, s51, v192
	v_cmp_ge_u32_e32 vcc, s80, v131
	v_cmp_lt_u32_e64 s[46:47], s80, v190
	s_and_b64 s[46:47], vcc, s[46:47]
	s_and_b64 vcc, s[10:11], s[46:47]
	s_waitcnt lgkmcnt(8)
	v_mfma_f32_32x32x16_bf16 v[2:17], v[40:43], v[44:47], v[2:17]
	ds_read_b128 v[40:43], v27 offset:17600
	ds_read_b128 v[44:47], v28 offset:192
	s_waitcnt lgkmcnt(8)
	v_mfma_f32_32x32x16_bf16 v[2:17], v[48:51], v[52:55], v[2:17]
	ds_read_b128 v[48:51], v27 offset:17632
	ds_read_b128 v[52:55], v28 offset:224
	s_waitcnt lgkmcnt(8)
	v_mfma_f32_32x32x16_bf16 v[2:17], v[56:59], v[60:63], v[2:17]
	s_waitcnt lgkmcnt(6)
	v_mfma_f32_32x32x16_bf16 v[2:17], v[18:21], v[22:25], v[2:17]
	s_waitcnt lgkmcnt(4)
	v_mfma_f32_32x32x16_bf16 v[2:17], v[32:35], v[36:39], v[2:17]
	s_waitcnt lgkmcnt(2)
	v_mfma_f32_32x32x16_bf16 v[2:17], v[40:43], v[44:47], v[2:17]
	s_waitcnt lgkmcnt(0)
	v_mfma_f32_32x32x16_bf16 v[2:17], v[48:51], v[52:55], v[2:17]
	v_and_b32_e32 v18, 3, v26
	v_add_u32_e32 v19, 0x51c, v193
	v_mul_u32_u24_e32 v18, 0x980, v18
	v_and_b32_e32 v19, -16, v19
	v_add3_u32 v30, s88, v18, v19
	ds_read_b128 v[22:25], v30
	ds_read_b128 v[26:29], v30 offset:32
	s_waitcnt lgkmcnt(1)
	s_nop 3
	v_fmamk_f32 v2, v2, 0x3e0293ee, v22
	v_cndmask_b32_e32 v21, v224, v2, vcc
	s_and_b64 vcc, s[46:47], s[12:13]
	v_fmamk_f32 v2, v3, 0x3e0293ee, v23
	v_cndmask_b32_e32 v20, v224, v2, vcc
	s_and_b64 vcc, s[46:47], s[14:15]
	v_fmamk_f32 v3, v4, 0x3e0293ee, v24
	v_cndmask_b32_e32 v19, v224, v3, vcc
	s_and_b64 vcc, s[46:47], s[16:17]
	v_fmac_f32_e32 v25, 0x3e0293ee, v5
	v_cndmask_b32_e32 v18, v224, v25, vcc
	ds_read_b128 v[22:25], v30 offset:64
	s_and_b64 vcc, s[46:47], s[18:19]
	s_waitcnt lgkmcnt(1)
	v_fmamk_f32 v3, v6, 0x3e0293ee, v26
	v_cndmask_b32_e32 v6, v224, v3, vcc
	s_and_b64 vcc, s[46:47], s[20:21]
	v_fmamk_f32 v3, v7, 0x3e0293ee, v27
	v_cndmask_b32_e32 v5, v224, v3, vcc
	s_and_b64 vcc, s[46:47], s[22:23]
	v_fmamk_f32 v3, v8, 0x3e0293ee, v28
	v_cndmask_b32_e32 v4, v224, v3, vcc
	s_and_b64 vcc, s[46:47], s[24:25]
	v_fmac_f32_e32 v29, 0x3e0293ee, v9
	v_cndmask_b32_e32 v3, v224, v29, vcc
	s_and_b64 vcc, s[26:27], s[46:47]
	s_waitcnt lgkmcnt(0)
	v_fmamk_f32 v7, v10, 0x3e0293ee, v22
	v_cndmask_b32_e32 v10, v224, v7, vcc
	s_and_b64 vcc, s[46:47], s[28:29]
	v_fmamk_f32 v7, v11, 0x3e0293ee, v23
	v_cndmask_b32_e32 v9, v224, v7, vcc
	s_and_b64 vcc, s[46:47], s[30:31]
	v_fmamk_f32 v7, v12, 0x3e0293ee, v24
	v_cndmask_b32_e32 v8, v224, v7, vcc
	s_and_b64 vcc, s[46:47], s[34:35]
	v_fmac_f32_e32 v25, 0x3e0293ee, v13
	v_cndmask_b32_e32 v7, v224, v25, vcc
	ds_read_b128 v[22:25], v30 offset:96
	v_max3_f32 v2, v21, s93, v20
	v_max3_f32 v2, v2, v19, v18
	s_and_b64 vcc, s[46:47], s[36:37]
	v_max3_f32 v2, v2, v6, v5
	s_waitcnt lgkmcnt(0)
	v_fmamk_f32 v11, v14, 0x3e0293ee, v22
	v_cndmask_b32_e32 v13, v224, v11, vcc
	s_and_b64 vcc, s[46:47], s[38:39]
	v_fmamk_f32 v11, v15, 0x3e0293ee, v23
	v_max3_f32 v2, v2, v4, v3
	v_cndmask_b32_e32 v11, v224, v11, vcc
	s_and_b64 vcc, s[46:47], s[40:41]
	v_fmamk_f32 v12, v16, 0x3e0293ee, v24
	v_max3_f32 v2, v2, v10, v9
	v_cndmask_b32_e32 v12, v224, v12, vcc
	s_and_b64 vcc, s[46:47], s[42:43]
	v_fmac_f32_e32 v25, 0x3e0293ee, v17
	v_max3_f32 v2, v2, v8, v7
	v_cndmask_b32_e32 v14, v224, v25, vcc
	v_cmp_lt_i32_e32 vcc, v223, v225
	v_max3_f32 v2, v2, v13, v11
	v_max3_f32 v2, v2, v12, v14
	v_cndmask_b32_e32 v15, v217, v223, vcc
	v_lshlrev_b32_e32 v15, 2, v15
	ds_bpermute_b32 v15, v15, v2
	s_waitcnt lgkmcnt(0)
	v_max3_f32 v195, v1, v2, v15
	v_sub_f32_e32 v1, v1, v195
	v_exp_f32_e32 v2, v1
	s_nop 0
	v_cmp_neq_f32_e32 vcc, 1.0, v2
	s_cbranch_vccz .LBB0_236
	v_pk_mul_f32 v[80:81], v[80:81], v[2:3] op_sel_hi:[1,0]
	v_pk_mul_f32 v[78:79], v[78:79], v[2:3] op_sel_hi:[1,0]
	v_pk_mul_f32 v[76:77], v[76:77], v[2:3] op_sel_hi:[1,0]
	v_pk_mul_f32 v[74:75], v[74:75], v[2:3] op_sel_hi:[1,0]
	v_pk_mul_f32 v[72:73], v[72:73], v[2:3] op_sel_hi:[1,0]
	v_pk_mul_f32 v[70:71], v[70:71], v[2:3] op_sel_hi:[1,0]
	v_pk_mul_f32 v[68:69], v[68:69], v[2:3] op_sel_hi:[1,0]
	v_pk_mul_f32 v[66:67], v[66:67], v[2:3] op_sel_hi:[1,0]
	v_pk_mul_f32 v[96:97], v[96:97], v[2:3] op_sel_hi:[1,0]
	v_pk_mul_f32 v[94:95], v[94:95], v[2:3] op_sel_hi:[1,0]
	v_pk_mul_f32 v[92:93], v[92:93], v[2:3] op_sel_hi:[1,0]
	v_pk_mul_f32 v[90:91], v[90:91], v[2:3] op_sel_hi:[1,0]
	v_pk_mul_f32 v[88:89], v[88:89], v[2:3] op_sel_hi:[1,0]
	v_pk_mul_f32 v[86:87], v[86:87], v[2:3] op_sel_hi:[1,0]
	v_pk_mul_f32 v[84:85], v[84:85], v[2:3] op_sel_hi:[1,0]
	v_pk_mul_f32 v[82:83], v[82:83], v[2:3] op_sel_hi:[1,0]
	v_pk_mul_f32 v[112:113], v[112:113], v[2:3] op_sel_hi:[1,0]
	v_pk_mul_f32 v[110:111], v[110:111], v[2:3] op_sel_hi:[1,0]
	v_pk_mul_f32 v[108:109], v[108:109], v[2:3] op_sel_hi:[1,0]
	v_pk_mul_f32 v[106:107], v[106:107], v[2:3] op_sel_hi:[1,0]
	v_pk_mul_f32 v[104:105], v[104:105], v[2:3] op_sel_hi:[1,0]
	v_pk_mul_f32 v[102:103], v[102:103], v[2:3] op_sel_hi:[1,0]
	v_pk_mul_f32 v[100:101], v[100:101], v[2:3] op_sel_hi:[1,0]
	v_pk_mul_f32 v[98:99], v[98:99], v[2:3] op_sel_hi:[1,0]
	v_pk_mul_f32 v[128:129], v[128:129], v[2:3] op_sel_hi:[1,0]
	v_pk_mul_f32 v[126:127], v[126:127], v[2:3] op_sel_hi:[1,0]
	v_pk_mul_f32 v[124:125], v[124:125], v[2:3] op_sel_hi:[1,0]
	v_pk_mul_f32 v[122:123], v[122:123], v[2:3] op_sel_hi:[1,0]
	v_pk_mul_f32 v[120:121], v[120:121], v[2:3] op_sel_hi:[1,0]
	v_pk_mul_f32 v[118:119], v[118:119], v[2:3] op_sel_hi:[1,0]
	v_pk_mul_f32 v[116:117], v[116:117], v[2:3] op_sel_hi:[1,0]
	v_pk_mul_f32 v[114:115], v[114:115], v[2:3] op_sel_hi:[1,0]
